# grid barrier: waiting workgroups poll their generation word every 3 sleep units instead of 1 (less traffic on the word being released)
# speedup vs baseline: 1.0303x; 1.0006x over previous
.LBB0_753:
	s_and_b32 s12, s16, 0xff
	s_mov_b64 s[10:11], -1
	s_cmp_lg_u32 s12, 0
	s_mov_b64 s[14:15], -1
	s_sleep 3
	s_cbranch_scc1 .LBB0_756
	v_readlane_b32 s12, v251, 59
	v_readlane_b32 s13, v251, 60
	s_nop 4
	global_load_dword v4, v3, s[12:13] sc1
	s_waitcnt vmcnt(0)
	v_cmp_eq_u32_e32 vcc, 0, v4
	s_cbranch_vccnz .LBB0_758
	s_mov_b64 s[14:15], 0
	s_mov_b64 s[12:13], -1
